# pre-attention rmsnorm (layers 1-3): next row prefetched into a second register set, counted waits
# baseline (speedup 1.0000x reference)
.LBB0_70:
	s_or_b64 exec, exec, s[4:5]
	v_readlane_b32 s4, v255, 10
	s_cmp_lg_u32 s4, 0
	v_readlane_b32 s5, v255, 11
	s_cbranch_scc0 .LBB0_75
	s_cmpk_gt_i32 s12, 0x7fff
	s_cbranch_scc1 .LBB0_74
	v_mov_b64_e32 v[6:7], s[14:15]
	global_load_dwordx2 v[6:7], v[6:7], off offset:16
	v_readlane_b32 s4, v255, 10
	v_lshlrev_b32_e32 v24, 3, v28
	s_lshl_b32 s74, s4, 10
	v_ashrrev_i32_e32 v25, 31, v24
	v_lshlrev_b64 v[26:27], 2, v[24:25]
	v_readlane_b32 s5, v255, 11
	s_ashr_i32 s13, s12, 31
	s_lshl_b64 s[4:5], s[12:13], 11
	v_lshl_add_u64 v[24:25], v[24:25], 1, s[4:5]
	s_waitcnt vmcnt(0) lgkmcnt(0)
	v_lshl_add_u64 v[24:25], v[4:5], 0, v[24:25]
	s_mov_b64 s[4:5], 0x2b89400
	v_lshl_add_u64 v[24:25], v[24:25], 0, s[4:5]
	s_lshl_b64 s[4:5], s[12:13], 12
	v_lshlrev_b32_e32 v32, 2, v28
	v_xor_b32_e32 v0, 0x80, v32
	v_xor_b32_e32 v23, 64, v32
	v_xor_b32_e32 v29, 32, v32
	v_xor_b32_e32 v30, 16, v32
	v_xor_b32_e32 v31, 8, v32
	v_xor_b32_e32 v32, 4, v32
	v_lshl_add_u64 v[6:7], s[74:75], 2, v[6:7]
	v_lshl_add_u64 v[18:19], v[6:7], 0, v[26:27]
	global_load_dwordx4 v[6:9], v[18:19], off
	global_load_dwordx4 v[10:13], v[18:19], off offset:16
	global_load_dwordx4 v[14:17], v[18:19], off offset:2048
	s_nop 0
	global_load_dwordx4 v[18:21], v[18:19], off offset:2064
	v_lshl_add_u64 v[26:27], s[4:5], 0, v[26:27]
	v_lshl_add_u64 v[26:27], v[2:3], 0, v[26:27]
	s_mov_b32 s4, s12
	global_load_dwordx4 v[34:37], v[26:27], off
	global_load_dwordx4 v[38:41], v[26:27], off offset:16
	global_load_dwordx4 v[42:45], v[26:27], off offset:2048
	global_load_dwordx4 v[46:49], v[26:27], off offset:2064
.LBB0_73:
	s_add_i32 s4, s4, s38
	s_cmp_lt_i32 s4, 0x8000
	s_cselect_b32 s100, s46, 0
	s_cselect_b32 s101, s47, 0
	v_lshl_add_u64 v[26:27], v[26:27], 0, s[100:101]
	global_load_dwordx4 v[68:71], v[26:27], off
	global_load_dwordx4 v[72:75], v[26:27], off offset:16
	global_load_dwordx4 v[76:79], v[26:27], off offset:2048
	global_load_dwordx4 v[80:83], v[26:27], off offset:2064
	v_add_co_u32_e32 v50, vcc, s83, v24
	s_nop 0
	v_addc_co_u32_e32 v51, vcc, -1, v25, vcc
	s_waitcnt vmcnt(4)
	v_mov_b32_e32 v54, v35
	v_mov_b32_e32 v55, v39
	v_mov_b32_e32 v52, v34
	v_mov_b32_e32 v53, v38
	v_mov_b32_e32 v62, v43
	v_mov_b32_e32 v63, v47
	v_pk_mul_f32 v[54:55], v[54:55], v[54:55]
	v_mov_b32_e32 v56, v36
	v_mov_b32_e32 v57, v40
	v_mov_b32_e32 v60, v42
	v_mov_b32_e32 v61, v46
	v_pk_mul_f32 v[62:63], v[62:63], v[62:63]
	v_pk_fma_f32 v[52:53], v[52:53], v[52:53], v[54:55]
	v_mov_b32_e32 v58, v37
	v_mov_b32_e32 v59, v41
	v_mov_b32_e32 v64, v44
	v_mov_b32_e32 v65, v48
	v_pk_fma_f32 v[54:55], v[60:61], v[60:61], v[62:63]
	v_pk_fma_f32 v[52:53], v[56:57], v[56:57], v[52:53]
	v_mov_b32_e32 v66, v45
	v_mov_b32_e32 v67, v49
	v_pk_fma_f32 v[54:55], v[64:65], v[64:65], v[54:55]
	v_pk_fma_f32 v[52:53], v[58:59], v[58:59], v[52:53]
	v_pk_fma_f32 v[54:55], v[66:67], v[66:67], v[54:55]
	v_add_f32_e32 v33, v52, v53
	v_add_f32_e32 v33, v33, v54
	v_add_f32_e32 v33, v33, v55
	ds_bpermute_b32 v52, v0, v33
	s_waitcnt lgkmcnt(0)
	v_add_f32_e32 v33, v33, v52
	ds_bpermute_b32 v52, v23, v33
	s_waitcnt lgkmcnt(0)
	v_add_f32_e32 v33, v33, v52
	ds_bpermute_b32 v52, v29, v33
	s_waitcnt lgkmcnt(0)
	v_add_f32_e32 v33, v33, v52
	ds_bpermute_b32 v52, v30, v33
	s_waitcnt lgkmcnt(0)
	v_add_f32_e32 v33, v33, v52
	ds_bpermute_b32 v52, v31, v33
	s_waitcnt lgkmcnt(0)
	v_add_f32_e32 v33, v33, v52
	ds_bpermute_b32 v52, v32, v33
	s_waitcnt lgkmcnt(0)
	v_add_f32_e32 v33, v33, v52
	v_fmamk_f32 v33, v33, 0x3a800000, v244
	v_mul_f32_e32 v52, 0x4b800000, v33
	v_cmp_gt_f32_e32 vcc, s82, v33
	s_nop 1
	v_cndmask_b32_e32 v33, v33, v52, vcc
	v_rsq_f32_e32 v33, v33
	s_nop 0
	v_mul_f32_e32 v52, 0x45800000, v33
	v_cndmask_b32_e32 v52, v33, v52, vcc
	v_pk_mul_f32 v[34:35], v[34:35], v[52:53] op_sel_hi:[1,0]
	v_pk_mul_f32 v[36:37], v[36:37], v[52:53] op_sel_hi:[1,0]
	v_pk_mul_f32 v[38:39], v[38:39], v[52:53] op_sel_hi:[1,0]
	v_pk_mul_f32 v[40:41], v[40:41], v[52:53] op_sel_hi:[1,0]
	v_pk_mul_f32 v[42:43], v[42:43], v[52:53] op_sel_hi:[1,0]
	v_pk_mul_f32 v[44:45], v[44:45], v[52:53] op_sel_hi:[1,0]
	v_pk_mul_f32 v[46:47], v[46:47], v[52:53] op_sel_hi:[1,0]
	v_pk_mul_f32 v[48:49], v[48:49], v[52:53] op_sel_hi:[1,0]
	v_pk_mul_f32 v[36:37], v[8:9], v[36:37]
	v_pk_mul_f32 v[34:35], v[6:7], v[34:35]
	v_pk_mul_f32 v[40:41], v[12:13], v[40:41]
	v_pk_mul_f32 v[38:39], v[10:11], v[38:39]
	v_pk_mul_f32 v[44:45], v[16:17], v[44:45]
	v_pk_mul_f32 v[42:43], v[14:15], v[42:43]
	v_pk_mul_f32 v[48:49], v[20:21], v[48:49]
	v_pk_mul_f32 v[46:47], v[18:19], v[46:47]
	v_cvt_pk_bf16_f32 v34, v34, v35
	v_cvt_pk_bf16_f32 v35, v36, v37
	v_cvt_pk_bf16_f32 v36, v38, v39
	v_cvt_pk_bf16_f32 v37, v40, v41
	v_cvt_pk_bf16_f32 v38, v42, v43
	v_cvt_pk_bf16_f32 v39, v44, v45
	v_cvt_pk_bf16_f32 v40, v46, v47
	v_cvt_pk_bf16_f32 v41, v48, v49
	global_store_dwordx4 v[50:51], v[34:37], off
	global_store_dwordx4 v[24:25], v[38:41], off
	v_lshl_add_u64 v[24:25], v[24:25], 0, s[68:69]
	s_cbranch_scc0 .Lrn0_exit
	s_add_i32 s4, s4, s38
	s_cmp_lt_i32 s4, 0x8000
	s_cselect_b32 s100, s46, 0
	s_cselect_b32 s101, s47, 0
	v_lshl_add_u64 v[26:27], v[26:27], 0, s[100:101]
	global_load_dwordx4 v[34:37], v[26:27], off
	global_load_dwordx4 v[38:41], v[26:27], off offset:16
	global_load_dwordx4 v[42:45], v[26:27], off offset:2048
	global_load_dwordx4 v[46:49], v[26:27], off offset:2064
	v_add_co_u32_e32 v50, vcc, s83, v24
	s_nop 0
	v_addc_co_u32_e32 v51, vcc, -1, v25, vcc
	s_waitcnt vmcnt(6)
	v_mov_b32_e32 v54, v69
	v_mov_b32_e32 v55, v73
	v_mov_b32_e32 v52, v68
	v_mov_b32_e32 v53, v72
	v_mov_b32_e32 v62, v77
	v_mov_b32_e32 v63, v81
	v_pk_mul_f32 v[54:55], v[54:55], v[54:55]
	v_mov_b32_e32 v56, v70
	v_mov_b32_e32 v57, v74
	v_mov_b32_e32 v60, v76
	v_mov_b32_e32 v61, v80
	v_pk_mul_f32 v[62:63], v[62:63], v[62:63]
	v_pk_fma_f32 v[52:53], v[52:53], v[52:53], v[54:55]
	v_mov_b32_e32 v58, v71
	v_mov_b32_e32 v59, v75
	v_mov_b32_e32 v64, v78
	v_mov_b32_e32 v65, v82
	v_pk_fma_f32 v[54:55], v[60:61], v[60:61], v[62:63]
	v_pk_fma_f32 v[52:53], v[56:57], v[56:57], v[52:53]
	v_mov_b32_e32 v66, v79
	v_mov_b32_e32 v67, v83
	v_pk_fma_f32 v[54:55], v[64:65], v[64:65], v[54:55]
	v_pk_fma_f32 v[52:53], v[58:59], v[58:59], v[52:53]
	v_pk_fma_f32 v[54:55], v[66:67], v[66:67], v[54:55]
	v_add_f32_e32 v33, v52, v53
	v_add_f32_e32 v33, v33, v54
	v_add_f32_e32 v33, v33, v55
	ds_bpermute_b32 v52, v0, v33
	s_waitcnt lgkmcnt(0)
	v_add_f32_e32 v33, v33, v52
	ds_bpermute_b32 v52, v23, v33
	s_waitcnt lgkmcnt(0)
	v_add_f32_e32 v33, v33, v52
	ds_bpermute_b32 v52, v29, v33
	s_waitcnt lgkmcnt(0)
	v_add_f32_e32 v33, v33, v52
	ds_bpermute_b32 v52, v30, v33
	s_waitcnt lgkmcnt(0)
	v_add_f32_e32 v33, v33, v52
	ds_bpermute_b32 v52, v31, v33
	s_waitcnt lgkmcnt(0)
	v_add_f32_e32 v33, v33, v52
	ds_bpermute_b32 v52, v32, v33
	s_waitcnt lgkmcnt(0)
	v_add_f32_e32 v33, v33, v52
	v_fmamk_f32 v33, v33, 0x3a800000, v244
	v_mul_f32_e32 v52, 0x4b800000, v33
	v_cmp_gt_f32_e32 vcc, s82, v33
	s_nop 1
	v_cndmask_b32_e32 v33, v33, v52, vcc
	v_rsq_f32_e32 v33, v33
	s_nop 0
	v_mul_f32_e32 v52, 0x45800000, v33
	v_cndmask_b32_e32 v52, v33, v52, vcc
	v_pk_mul_f32 v[68:69], v[68:69], v[52:53] op_sel_hi:[1,0]
	v_pk_mul_f32 v[70:71], v[70:71], v[52:53] op_sel_hi:[1,0]
	v_pk_mul_f32 v[72:73], v[72:73], v[52:53] op_sel_hi:[1,0]
	v_pk_mul_f32 v[74:75], v[74:75], v[52:53] op_sel_hi:[1,0]
	v_pk_mul_f32 v[76:77], v[76:77], v[52:53] op_sel_hi:[1,0]
	v_pk_mul_f32 v[78:79], v[78:79], v[52:53] op_sel_hi:[1,0]
	v_pk_mul_f32 v[80:81], v[80:81], v[52:53] op_sel_hi:[1,0]
	v_pk_mul_f32 v[82:83], v[82:83], v[52:53] op_sel_hi:[1,0]
	v_pk_mul_f32 v[70:71], v[8:9], v[70:71]
	v_pk_mul_f32 v[68:69], v[6:7], v[68:69]
	v_pk_mul_f32 v[74:75], v[12:13], v[74:75]
	v_pk_mul_f32 v[72:73], v[10:11], v[72:73]
	v_pk_mul_f32 v[78:79], v[16:17], v[78:79]
	v_pk_mul_f32 v[76:77], v[14:15], v[76:77]
	v_pk_mul_f32 v[82:83], v[20:21], v[82:83]
	v_pk_mul_f32 v[80:81], v[18:19], v[80:81]
	v_cvt_pk_bf16_f32 v68, v68, v69
	v_cvt_pk_bf16_f32 v69, v70, v71
	v_cvt_pk_bf16_f32 v70, v72, v73
	v_cvt_pk_bf16_f32 v71, v74, v75
	v_cvt_pk_bf16_f32 v72, v76, v77
	v_cvt_pk_bf16_f32 v73, v78, v79
	v_cvt_pk_bf16_f32 v74, v80, v81
	v_cvt_pk_bf16_f32 v75, v82, v83
	global_store_dwordx4 v[50:51], v[68:71], off
	global_store_dwordx4 v[24:25], v[72:75], off
	v_lshl_add_u64 v[24:25], v[24:25], 0, s[68:69]
	s_cbranch_scc1 .LBB0_73
.Lrn0_exit:
.LBB0_74:
	s_cbranch_execz .LBB0_76
	s_branch .LBB0_94
